# NA2 QK: batched K-fragment loads (10+6 tiles) instead of one round trip per key tile
# speedup vs baseline: 1.0084x; 1.0084x over previous
; __device__ __forceinline__ f32x4 mfma16(bf16x8 a, bf16x8 b, f32x4 c) { return __builtin_amdgcn_mfma_f32_16x16x32_bf16(a, b, c, 0, 0, 0); }
; __device__ void ph_na2(const P& p, LAS unsigned char* lds) {
;     ...
;             for (int hf = 0; hf < 2; ++hf) {
;                 f32x4 sc[16];
; #pragma unroll
;                 for (int kt = 0; kt < 16; ++kt) {
;                     const int a = kt >> 1, chh = kt & 1;
;                     const bf16_t* kp = hf ? kc : kl;
;                     if (hf) kc += 16 * 512; else kl += (chh ? 48 : 16) * 512;
;                     const bf16x8 A0 = *(const bf16x8*)kp, A1 = *(const bf16x8*)(kp + 32);
;                     f32x4 acc = {0.f, 0.f, 0.f, 0.f};
;                     acc = mfma16(A0, qf[0], acc); acc = mfma16(A1, qf[1], acc);
;                     if (hf == 0) {
; #pragma unroll
;                         for (int j = 0; j < 4; ++j) acc[j] = acc[j] * 0.18033688011112042f + rrow[a * 32 + crm[chh][j]];
;                     } else acc = acc * 0.18033688011112042f;
;                     sc[kt] = acc;
;                     if ((kt & 7) == 7) asm volatile("" : "+v"(kl), "+v"(kc) :: "memory");
;                 }
.LBB0_345:
	s_xor_b64 s[12:13], s[18:19], -1
	v_cndmask_b32_e64 v191, v111, v109, s[18:19]
	v_cndmask_b32_e64 v190, v110, v108, s[18:19]
	s_and_b64 s[4:5], s[18:19], exec
	s_mov_b32 s16, 0x4000
	s_cselect_b32 s16, 0xc000, s16
	s_mov_b32 s17, 0
	s_mov_b32 s14, 0x4000
	s_mov_b32 s15, 0
	s_waitcnt lgkmcnt(0)
	global_load_dwordx4 v[84:87], v[190:191], off
	global_load_dwordx4 v[44:47], v[190:191], off offset:64
	v_lshl_add_u64 v[202:203], v[190:191], 0, s[14:15]
	global_load_dwordx4 v[88:91], v[202:203], off
	global_load_dwordx4 v[48:51], v[202:203], off offset:64
	v_lshl_add_u64 v[190:191], v[202:203], 0, s[16:17]
	global_load_dwordx4 v[92:95], v[190:191], off
	global_load_dwordx4 v[52:55], v[190:191], off offset:64
	v_lshl_add_u64 v[202:203], v[190:191], 0, s[14:15]
	global_load_dwordx4 v[96:99], v[202:203], off
	global_load_dwordx4 v[56:59], v[202:203], off offset:64
	v_lshl_add_u64 v[190:191], v[202:203], 0, s[16:17]
	global_load_dwordx4 v[100:103], v[190:191], off
	global_load_dwordx4 v[60:63], v[190:191], off offset:64
	v_lshl_add_u64 v[202:203], v[190:191], 0, s[14:15]
	global_load_dwordx4 v[104:107], v[202:203], off
	global_load_dwordx4 v[64:67], v[202:203], off offset:64
	v_lshl_add_u64 v[190:191], v[202:203], 0, s[16:17]
	global_load_dwordx4 v[124:127], v[190:191], off
	global_load_dwordx4 v[68:71], v[190:191], off offset:64
	v_lshl_add_u64 v[202:203], v[190:191], 0, s[14:15]
	global_load_dwordx4 v[164:167], v[202:203], off
	global_load_dwordx4 v[72:75], v[202:203], off offset:64
	v_lshl_add_u64 v[190:191], v[202:203], 0, s[16:17]
	global_load_dwordx4 v[194:197], v[190:191], off
	global_load_dwordx4 v[76:79], v[190:191], off offset:64
	v_lshl_add_u64 v[202:203], v[190:191], 0, s[14:15]
	global_load_dwordx4 v[244:247], v[202:203], off
	global_load_dwordx4 v[80:83], v[202:203], off offset:64
	v_lshl_add_u64 v[190:191], v[202:203], 0, s[16:17]
	s_waitcnt vmcnt(18)
	v_mfma_f32_16x16x32_bf16 v[84:87], v[84:87], v[24:27], 0
	v_mfma_f32_16x16x32_bf16 v[44:47], v[44:47], v[20:23], v[84:87]
	s_waitcnt vmcnt(16)
	v_mfma_f32_16x16x32_bf16 v[88:91], v[88:91], v[24:27], 0
	v_mfma_f32_16x16x32_bf16 v[48:51], v[48:51], v[20:23], v[88:91]
	s_waitcnt vmcnt(14)
	v_mfma_f32_16x16x32_bf16 v[92:95], v[92:95], v[24:27], 0
	v_mfma_f32_16x16x32_bf16 v[52:55], v[52:55], v[20:23], v[92:95]
	s_waitcnt vmcnt(12)
	v_mfma_f32_16x16x32_bf16 v[96:99], v[96:99], v[24:27], 0
	v_mfma_f32_16x16x32_bf16 v[56:59], v[56:59], v[20:23], v[96:99]
	s_waitcnt vmcnt(10)
	v_mfma_f32_16x16x32_bf16 v[100:103], v[100:103], v[24:27], 0
	v_mfma_f32_16x16x32_bf16 v[60:63], v[60:63], v[20:23], v[100:103]
	s_waitcnt vmcnt(8)
	v_mfma_f32_16x16x32_bf16 v[104:107], v[104:107], v[24:27], 0
	v_mfma_f32_16x16x32_bf16 v[64:67], v[64:67], v[20:23], v[104:107]
	s_waitcnt vmcnt(6)
	v_mfma_f32_16x16x32_bf16 v[124:127], v[124:127], v[24:27], 0
	v_mfma_f32_16x16x32_bf16 v[68:71], v[68:71], v[20:23], v[124:127]
	s_waitcnt vmcnt(4)
	v_mfma_f32_16x16x32_bf16 v[164:167], v[164:167], v[24:27], 0
	v_mfma_f32_16x16x32_bf16 v[72:75], v[72:75], v[20:23], v[164:167]
	s_waitcnt vmcnt(2)
	v_mfma_f32_16x16x32_bf16 v[194:197], v[194:197], v[24:27], 0
	v_mfma_f32_16x16x32_bf16 v[76:79], v[76:79], v[20:23], v[194:197]
	s_waitcnt vmcnt(0)
	v_mfma_f32_16x16x32_bf16 v[244:247], v[244:247], v[24:27], 0
	v_mfma_f32_16x16x32_bf16 v[80:83], v[80:83], v[20:23], v[244:247]
	global_load_dwordx4 v[124:127], v[190:191], off
	global_load_dwordx4 v[84:87], v[190:191], off offset:64
	v_lshl_add_u64 v[202:203], v[190:191], 0, s[14:15]
	global_load_dwordx4 v[164:167], v[202:203], off
	global_load_dwordx4 v[88:91], v[202:203], off offset:64
	v_lshl_add_u64 v[190:191], v[202:203], 0, s[16:17]
	global_load_dwordx4 v[194:197], v[190:191], off
	global_load_dwordx4 v[92:95], v[190:191], off offset:64
	v_lshl_add_u64 v[202:203], v[190:191], 0, s[14:15]
	global_load_dwordx4 v[244:247], v[202:203], off
	global_load_dwordx4 v[96:99], v[202:203], off offset:64
	v_lshl_add_u64 v[190:191], v[202:203], 0, s[16:17]
	global_load_dwordx4 v[204:207], v[190:191], off
	global_load_dwordx4 v[100:103], v[190:191], off offset:64
	v_lshl_add_u64 v[202:203], v[190:191], 0, s[14:15]
	global_load_dwordx4 v[208:211], v[202:203], off
	global_load_dwordx4 v[104:107], v[202:203], off offset:64
	s_waitcnt vmcnt(10)
	v_mfma_f32_16x16x32_bf16 v[124:127], v[124:127], v[24:27], 0
	v_mfma_f32_16x16x32_bf16 v[84:87], v[84:87], v[20:23], v[124:127]
	s_waitcnt vmcnt(8)
	v_mfma_f32_16x16x32_bf16 v[164:167], v[164:167], v[24:27], 0
	v_mfma_f32_16x16x32_bf16 v[88:91], v[88:91], v[20:23], v[164:167]
	s_waitcnt vmcnt(6)
	v_mfma_f32_16x16x32_bf16 v[194:197], v[194:197], v[24:27], 0
	v_mfma_f32_16x16x32_bf16 v[92:95], v[92:95], v[20:23], v[194:197]
	s_waitcnt vmcnt(4)
	v_mfma_f32_16x16x32_bf16 v[244:247], v[244:247], v[24:27], 0
	v_mfma_f32_16x16x32_bf16 v[96:99], v[96:99], v[20:23], v[244:247]
	s_waitcnt vmcnt(2)
	v_mfma_f32_16x16x32_bf16 v[204:207], v[204:207], v[24:27], 0
	v_mfma_f32_16x16x32_bf16 v[100:103], v[100:103], v[20:23], v[204:207]
	s_waitcnt vmcnt(0)
	v_mfma_f32_16x16x32_bf16 v[208:211], v[208:211], v[24:27], 0
	v_mfma_f32_16x16x32_bf16 v[104:107], v[104:107], v[20:23], v[208:211]
	s_nop 7
	s_and_b64 vcc, exec, s[12:13]
	s_cbranch_vccz .Lna_qk_local
; __device__ void ph_na2(const P& p, LAS unsigned char* lds) {
;     ...
;                     if (hf == 0) {
; #pragma unroll
;                         for (int j = 0; j < 4; ++j) acc[j] = acc[j] * 0.18033688011112042f + rrow[a * 32 + crm[chh][j]];
;                     } else acc = acc * 0.18033688011112042f;
	v_pk_mul_f32 v[46:47], v[46:47], s[64:65] op_sel_hi:[1,0]
	v_pk_mul_f32 v[44:45], v[44:45], s[64:65] op_sel_hi:[1,0]
	v_pk_mul_f32 v[50:51], v[50:51], s[64:65] op_sel_hi:[1,0]
	v_pk_mul_f32 v[48:49], v[48:49], s[64:65] op_sel_hi:[1,0]
	v_pk_mul_f32 v[54:55], v[54:55], s[64:65] op_sel_hi:[1,0]
	v_pk_mul_f32 v[52:53], v[52:53], s[64:65] op_sel_hi:[1,0]
	v_pk_mul_f32 v[58:59], v[58:59], s[64:65] op_sel_hi:[1,0]
	v_pk_mul_f32 v[56:57], v[56:57], s[64:65] op_sel_hi:[1,0]
	v_pk_mul_f32 v[62:63], v[62:63], s[64:65] op_sel_hi:[1,0]
	v_pk_mul_f32 v[60:61], v[60:61], s[64:65] op_sel_hi:[1,0]
	v_pk_mul_f32 v[66:67], v[66:67], s[64:65] op_sel_hi:[1,0]
	v_pk_mul_f32 v[64:65], v[64:65], s[64:65] op_sel_hi:[1,0]
	v_pk_mul_f32 v[70:71], v[70:71], s[64:65] op_sel_hi:[1,0]
	v_pk_mul_f32 v[68:69], v[68:69], s[64:65] op_sel_hi:[1,0]
	v_pk_mul_f32 v[74:75], v[74:75], s[64:65] op_sel_hi:[1,0]
	v_pk_mul_f32 v[72:73], v[72:73], s[64:65] op_sel_hi:[1,0]
	v_pk_mul_f32 v[78:79], v[78:79], s[64:65] op_sel_hi:[1,0]
	v_pk_mul_f32 v[76:77], v[76:77], s[64:65] op_sel_hi:[1,0]
	v_pk_mul_f32 v[82:83], v[82:83], s[64:65] op_sel_hi:[1,0]
	v_pk_mul_f32 v[80:81], v[80:81], s[64:65] op_sel_hi:[1,0]
	v_pk_mul_f32 v[86:87], v[86:87], s[64:65] op_sel_hi:[1,0]
	v_pk_mul_f32 v[84:85], v[84:85], s[64:65] op_sel_hi:[1,0]
	v_pk_mul_f32 v[90:91], v[90:91], s[64:65] op_sel_hi:[1,0]
	v_pk_mul_f32 v[88:89], v[88:89], s[64:65] op_sel_hi:[1,0]
	v_pk_mul_f32 v[94:95], v[94:95], s[64:65] op_sel_hi:[1,0]
	v_pk_mul_f32 v[92:93], v[92:93], s[64:65] op_sel_hi:[1,0]
	v_pk_mul_f32 v[98:99], v[98:99], s[64:65] op_sel_hi:[1,0]
	v_pk_mul_f32 v[96:97], v[96:97], s[64:65] op_sel_hi:[1,0]
	v_pk_mul_f32 v[102:103], v[102:103], s[64:65] op_sel_hi:[1,0]
	v_pk_mul_f32 v[100:101], v[100:101], s[64:65] op_sel_hi:[1,0]
	v_pk_mul_f32 v[106:107], v[106:107], s[64:65] op_sel_hi:[1,0]
	v_pk_mul_f32 v[104:105], v[104:105], s[64:65] op_sel_hi:[1,0]
	v_mov_b32_e32 v205, v170
	v_mov_b32_e32 v206, v161
	v_mov_b32_e32 v207, v160
	v_mov_b32_e32 v208, v159
	v_mov_b32_e32 v209, v158
	v_mov_b32_e32 v210, v157
	v_mov_b32_e32 v211, v156
	v_mov_b32_e32 v212, v155
	s_branch .Lna_qk_done
.Lna_qk_local:
	ds_read_b32 v124, v3 offset:896
	ds_read_b32 v126, v175 offset:896
	ds_read_b32 v127, v176 offset:896
	ds_read_b32 v125, v123 offset:896
	ds_read_b32 v164, v177 offset:896
	ds_read_b32 v166, v179 offset:896
	ds_read_b32 v167, v180 offset:896
	ds_read_b32 v165, v178 offset:896
	ds_read_b32 v194, v3 offset:1024
	ds_read_b32 v196, v175 offset:1024
	ds_read_b32 v197, v176 offset:1024
	ds_read_b32 v195, v123 offset:1024
	s_waitcnt lgkmcnt(8)
	v_pk_fma_f32 v[46:47], v[46:47], s[64:65], v[126:127] op_sel_hi:[1,0,1]
	v_pk_fma_f32 v[44:45], v[44:45], s[64:65], v[124:125] op_sel_hi:[1,0,1]
	ds_read_b32 v244, v177 offset:1024
	ds_read_b32 v246, v179 offset:1024
	ds_read_b32 v247, v180 offset:1024
	ds_read_b32 v245, v178 offset:1024
	s_waitcnt lgkmcnt(8)
	v_pk_fma_f32 v[50:51], v[50:51], s[64:65], v[166:167] op_sel_hi:[1,0,1]
	v_pk_fma_f32 v[48:49], v[48:49], s[64:65], v[164:165] op_sel_hi:[1,0,1]
	ds_read_b32 v124, v3 offset:1152
	ds_read_b32 v126, v175 offset:1152
	ds_read_b32 v127, v176 offset:1152
	ds_read_b32 v125, v123 offset:1152
	s_waitcnt lgkmcnt(8)
	v_pk_fma_f32 v[54:55], v[54:55], s[64:65], v[196:197] op_sel_hi:[1,0,1]
	v_pk_fma_f32 v[52:53], v[52:53], s[64:65], v[194:195] op_sel_hi:[1,0,1]
	ds_read_b32 v164, v177 offset:1152
	ds_read_b32 v166, v179 offset:1152
	ds_read_b32 v167, v180 offset:1152
	ds_read_b32 v165, v178 offset:1152
	s_waitcnt lgkmcnt(8)
	v_pk_fma_f32 v[58:59], v[58:59], s[64:65], v[246:247] op_sel_hi:[1,0,1]
	v_pk_fma_f32 v[56:57], v[56:57], s[64:65], v[244:245] op_sel_hi:[1,0,1]
	ds_read_b32 v194, v3 offset:1280
	ds_read_b32 v196, v175 offset:1280
	ds_read_b32 v197, v176 offset:1280
	ds_read_b32 v195, v123 offset:1280
	s_waitcnt lgkmcnt(8)
	v_pk_fma_f32 v[62:63], v[62:63], s[64:65], v[126:127] op_sel_hi:[1,0,1]
	v_pk_fma_f32 v[60:61], v[60:61], s[64:65], v[124:125] op_sel_hi:[1,0,1]
	ds_read_b32 v244, v177 offset:1280
	ds_read_b32 v246, v179 offset:1280
	ds_read_b32 v247, v180 offset:1280
	ds_read_b32 v245, v178 offset:1280
	s_waitcnt lgkmcnt(8)
	v_pk_fma_f32 v[66:67], v[66:67], s[64:65], v[166:167] op_sel_hi:[1,0,1]
	v_pk_fma_f32 v[64:65], v[64:65], s[64:65], v[164:165] op_sel_hi:[1,0,1]
	ds_read_b32 v124, v3 offset:1408
	ds_read_b32 v126, v175 offset:1408
	ds_read_b32 v127, v176 offset:1408
	ds_read_b32 v125, v123 offset:1408
	s_waitcnt lgkmcnt(8)
	v_pk_fma_f32 v[70:71], v[70:71], s[64:65], v[196:197] op_sel_hi:[1,0,1]
	v_pk_fma_f32 v[68:69], v[68:69], s[64:65], v[194:195] op_sel_hi:[1,0,1]
	ds_read_b32 v164, v177 offset:1408
	ds_read_b32 v166, v179 offset:1408
	ds_read_b32 v167, v180 offset:1408
	ds_read_b32 v165, v178 offset:1408
	s_waitcnt lgkmcnt(8)
	v_pk_fma_f32 v[74:75], v[74:75], s[64:65], v[246:247] op_sel_hi:[1,0,1]
	v_pk_fma_f32 v[72:73], v[72:73], s[64:65], v[244:245] op_sel_hi:[1,0,1]
	ds_read_b32 v194, v3 offset:1536
	ds_read_b32 v196, v175 offset:1536
	ds_read_b32 v197, v176 offset:1536
	ds_read_b32 v195, v123 offset:1536
	s_waitcnt lgkmcnt(8)
	v_pk_fma_f32 v[78:79], v[78:79], s[64:65], v[126:127] op_sel_hi:[1,0,1]
	v_pk_fma_f32 v[76:77], v[76:77], s[64:65], v[124:125] op_sel_hi:[1,0,1]
	ds_read_b32 v244, v177 offset:1536
	ds_read_b32 v246, v179 offset:1536
	ds_read_b32 v247, v180 offset:1536
	ds_read_b32 v245, v178 offset:1536
	s_waitcnt lgkmcnt(8)
	v_pk_fma_f32 v[82:83], v[82:83], s[64:65], v[166:167] op_sel_hi:[1,0,1]
	v_pk_fma_f32 v[80:81], v[80:81], s[64:65], v[164:165] op_sel_hi:[1,0,1]
	ds_read_b32 v124, v3 offset:1664
	ds_read_b32 v126, v175 offset:1664
	ds_read_b32 v127, v176 offset:1664
	ds_read_b32 v125, v123 offset:1664
	s_waitcnt lgkmcnt(8)
; __device__ void ph_na2(const P& p, LAS unsigned char* lds) {
;     ...
;                     if (hf == 0) {
; #pragma unroll
;                         for (int j = 0; j < 4; ++j) acc[j] = acc[j] * 0.18033688011112042f + rrow[a * 32 + crm[chh][j]];
;                     } else acc = acc * 0.18033688011112042f;
;                     sc[kt] = acc;
;                     if ((kt & 7) == 7) asm volatile("" : "+v"(kl), "+v"(kc) :: "memory");
;                 }
;                 float m = -1e30f;
; #pragma unroll
;                 for (int kt = 0; kt < 16; ++kt) m = fmaxf(m, fmaxf(fmaxf(sc[kt][0], sc[kt][1]), fmaxf(sc[kt][2], sc[kt][3])));
;                 m = fmaxf(m, __shfl_xor(m, 16)); m = fmaxf(m, __shfl_xor(m, 32));
	v_pk_fma_f32 v[86:87], v[86:87], s[64:65], v[196:197] op_sel_hi:[1,0,1]
	v_pk_fma_f32 v[84:85], v[84:85], s[64:65], v[194:195] op_sel_hi:[1,0,1]
	ds_read_b32 v164, v177 offset:1664
	ds_read_b32 v166, v179 offset:1664
	ds_read_b32 v167, v180 offset:1664
	ds_read_b32 v165, v178 offset:1664
	s_waitcnt lgkmcnt(8)
	v_pk_fma_f32 v[90:91], v[90:91], s[64:65], v[246:247] op_sel_hi:[1,0,1]
	v_pk_fma_f32 v[88:89], v[88:89], s[64:65], v[244:245] op_sel_hi:[1,0,1]
	ds_read_b32 v194, v3 offset:1792
	ds_read_b32 v196, v175 offset:1792
	ds_read_b32 v197, v176 offset:1792
	ds_read_b32 v195, v123 offset:1792
	s_waitcnt lgkmcnt(8)
	v_pk_fma_f32 v[94:95], v[94:95], s[64:65], v[126:127] op_sel_hi:[1,0,1]
	v_pk_fma_f32 v[92:93], v[92:93], s[64:65], v[124:125] op_sel_hi:[1,0,1]
	ds_read_b32 v244, v177 offset:1792
	ds_read_b32 v246, v179 offset:1792
	ds_read_b32 v247, v180 offset:1792
	ds_read_b32 v245, v178 offset:1792
	s_waitcnt lgkmcnt(8)
	v_pk_fma_f32 v[98:99], v[98:99], s[64:65], v[166:167] op_sel_hi:[1,0,1]
	v_pk_fma_f32 v[96:97], v[96:97], s[64:65], v[164:165] op_sel_hi:[1,0,1]
	s_waitcnt lgkmcnt(4)
	v_pk_fma_f32 v[102:103], v[102:103], s[64:65], v[196:197] op_sel_hi:[1,0,1]
	v_pk_fma_f32 v[100:101], v[100:101], s[64:65], v[194:195] op_sel_hi:[1,0,1]
	s_waitcnt lgkmcnt(0)
	v_pk_fma_f32 v[106:107], v[106:107], s[64:65], v[246:247] op_sel_hi:[1,0,1]
	v_pk_fma_f32 v[104:105], v[104:105], s[64:65], v[244:245] op_sel_hi:[1,0,1]
	v_mov_b32_e32 v205, v188
	v_mov_b32_e32 v206, v187
	v_mov_b32_e32 v207, v186
	v_mov_b32_e32 v208, v185
	v_mov_b32_e32 v209, v184
	v_mov_b32_e32 v210, v183
	v_mov_b32_e32 v211, v182
	v_mov_b32_e32 v212, v181
.Lna_qk_done:
	v_max_f32_e32 v124, v47, v47
	v_max_f32_e32 v125, v46, v46
	v_max_f32_e32 v124, v125, v124
	v_max_f32_e32 v125, v51, v51
	v_max_f32_e32 v126, v50, v50
	v_max_f32_e32 v125, v126, v125
	v_max3_f32 v124, v44, v45, v124
	v_max3_f32 v125, v48, v49, v125
	s_mov_b32 s4, 0xf149f2ca
	v_max3_f32 v124, v124, s4, v125
	v_max_f32_e32 v125, v55, v55
	v_max_f32_e32 v126, v54, v54
	v_max_f32_e32 v125, v126, v125
	v_max_f32_e32 v126, v59, v59
	v_max_f32_e32 v127, v58, v58
	v_max_f32_e32 v126, v127, v126
	v_max3_f32 v125, v52, v53, v125
	v_max3_f32 v126, v56, v57, v126
	v_max3_f32 v124, v124, v125, v126
	v_max_f32_e32 v125, v63, v63
	v_max_f32_e32 v126, v62, v62
	v_max_f32_e32 v125, v126, v125
	v_max_f32_e32 v126, v67, v67
	v_max_f32_e32 v127, v66, v66
	v_max_f32_e32 v126, v127, v126
	v_max3_f32 v125, v60, v61, v125
	v_max3_f32 v126, v64, v65, v126
	v_max3_f32 v124, v124, v125, v126
	v_max_f32_e32 v125, v71, v71
	v_max_f32_e32 v126, v70, v70
	v_max_f32_e32 v125, v126, v125
	v_max_f32_e32 v126, v75, v75
	v_max_f32_e32 v127, v74, v74
	v_max_f32_e32 v126, v127, v126
	v_max3_f32 v125, v68, v69, v125
	v_max3_f32 v126, v72, v73, v126
	v_max3_f32 v124, v124, v125, v126
	v_max_f32_e32 v125, v79, v79
	v_max_f32_e32 v126, v78, v78
	v_max_f32_e32 v125, v126, v125
	v_max_f32_e32 v126, v83, v83
	v_max_f32_e32 v127, v82, v82
	v_max_f32_e32 v126, v127, v126
	v_max3_f32 v125, v76, v77, v125
	v_max3_f32 v126, v80, v81, v126
	v_max3_f32 v124, v124, v125, v126
	v_max_f32_e32 v125, v87, v87
	v_max_f32_e32 v126, v86, v86
	v_max_f32_e32 v125, v126, v125
	v_max_f32_e32 v126, v91, v91
	v_max_f32_e32 v127, v90, v90
	v_max_f32_e32 v126, v127, v126
	v_max3_f32 v125, v84, v85, v125
	v_max3_f32 v126, v88, v89, v126
	v_max3_f32 v124, v124, v125, v126
	v_max_f32_e32 v125, v95, v95
	v_max_f32_e32 v126, v94, v94
	v_max_f32_e32 v125, v126, v125
	v_max_f32_e32 v126, v99, v99
	v_max_f32_e32 v127, v98, v98
	v_max_f32_e32 v126, v127, v126
	v_max3_f32 v125, v92, v93, v125
	v_max3_f32 v126, v96, v97, v126
	v_max3_f32 v124, v124, v125, v126
	v_max_f32_e32 v125, v103, v103
	v_max_f32_e32 v126, v102, v102
	v_max_f32_e32 v125, v126, v125
	v_max_f32_e32 v126, v107, v107
	v_max_f32_e32 v127, v106, v106
	v_max_f32_e32 v126, v127, v126
	v_max3_f32 v125, v100, v101, v125
	v_max3_f32 v126, v104, v105, v126
	v_max3_f32 v124, v124, v125, v126
	v_and_b32_e32 v126, 64, v193
	v_xor_b32_e32 v125, 16, v193
	v_add_u32_e32 v126, 64, v126
	v_cmp_lt_i32_e32 vcc, v125, v126
	s_mov_b64 s[18:19], 0
	s_nop 0
	v_cndmask_b32_e32 v125, v193, v125, vcc
	v_lshlrev_b32_e32 v237, 2, v125
	ds_bpermute_b32 v125, v237, v124
	s_waitcnt lgkmcnt(0)
	v_max_f32_e32 v125, v125, v125
	v_max_f32_e32 v124, v124, v125
	v_xor_b32_e32 v125, 32, v193
	v_cmp_lt_i32_e32 vcc, v125, v126
	s_nop 1
	v_cndmask_b32_e32 v125, v193, v125, vcc
	v_lshlrev_b32_e32 v239, 2, v125
	ds_bpermute_b32 v125, v239, v124
	s_and_b64 vcc, exec, s[12:13]
	s_waitcnt lgkmcnt(0)
; #define LAS __attribute__((address_space(3)))
; __device__ __forceinline__ s16x4 ds_tr(LAS unsigned char* a) { return __builtin_amdgcn_ds_read_tr16_b64_v4i16((LAS s16x4*)a); }
; __device__ __forceinline__ bf16x8 cat8(s16x4 lo, s16x4 hi) { return __builtin_shufflevector(lo, hi, 0, 1, 2, 3, 4, 5, 6, 7); }
; __device__ __forceinline__ f32x4 mfma16(bf16x8 a, bf16x8 b, f32x4 c) { return __builtin_amdgcn_mfma_f32_16x16x32_bf16(a, b, c, 0, 0, 0); }
; __device__ __forceinline__ bf16x8 pk8(f32x4 a, f32x4 b) { u32x4 w; w[0] = cvt_pk_bf16(a[0], a[1]); w[1] = cvt_pk_bf16(a[2], a[3]); w[2] = cvt_pk_bf16(b[0], b[1]); w[3] = cvt_pk_bf16(b[2], b[3]); return __builtin_bit_cast(bf16x8, w); }
; __device__ void ph_na2(const P& p, LAS unsigned char* lds) {
;     ...
;                 const float mn = fmaxf(M, m), es = __builtin_amdgcn_exp2f(M - mn);
;                 float l = 0.f;
; #pragma unroll
;                 for (int kt = 0; kt < 16; ++kt) {
; #pragma unroll
;                     for (int j = 0; j < 4; ++j) { const float e = __builtin_amdgcn_exp2f(sc[kt][j] - mn); sc[kt][j] = e; l += e; } }
;                 l += __shfl_xor(l, 16); l += __shfl_xor(l, 32);
;                 L = L * es + l; M = mn;
; #pragma unroll
;                 for (int dt = 0; dt < 4; ++dt) o[dt] = o[dt] * es;
; #pragma unroll
;                 for (int kp = 0; kp < 8; ++kp) {
;                     const bf16x8 pf = pk8(sc[2 * kp], sc[2 * kp + 1]);
;                     LAS unsigned char* vb = hf ? (Vc + (32 * kp + 4 * g + qq) * VP + 8 * pp) : (Vl + ((((r0 + kp) % RING) * 64) + cstart + 4 * g + qq) * VP + 8 * pp);
; #pragma unroll
;                     for (int dt = 0; dt < 4; ++dt) { const s16x4 lo = ds_tr(vb + dt * 32), hi = ds_tr(vb + 16 * VP + dt * 32); o[dt] = mfma16(cat8(lo, hi), pf, o[dt]); }
	v_max3_f32 v124, v0, v124, v125
	v_sub_f32_e32 v44, v44, v124
	v_exp_f32_e32 v234, v44
	v_sub_f32_e32 v45, v45, v124
	v_exp_f32_e32 v235, v45
	v_sub_f32_e32 v45, v46, v124
	v_exp_f32_e32 v236, v45
	v_sub_f32_e32 v45, v47, v124
	v_exp_f32_e32 v238, v45
	v_sub_f32_e32 v45, v48, v124
	v_add_f32_e32 v44, 0, v234
	v_exp_f32_e32 v240, v45
	v_sub_f32_e32 v45, v49, v124
	v_add_f32_e32 v44, v235, v44
	v_exp_f32_e32 v241, v45
	v_sub_f32_e32 v45, v50, v124
	v_add_f32_e32 v44, v236, v44
	v_exp_f32_e32 v242, v45
	v_sub_f32_e32 v45, v51, v124
	v_add_f32_e32 v44, v238, v44
	v_exp_f32_e32 v243, v45
	v_sub_f32_e32 v45, v52, v124
	v_add_f32_e32 v44, v240, v44
	v_exp_f32_e32 v225, v45
	v_sub_f32_e32 v45, v53, v124
	v_add_f32_e32 v44, v241, v44
	v_exp_f32_e32 v227, v45
	v_sub_f32_e32 v45, v54, v124
	v_add_f32_e32 v44, v242, v44
	v_exp_f32_e32 v228, v45
	v_sub_f32_e32 v45, v55, v124
	v_add_f32_e32 v44, v243, v44
	v_exp_f32_e32 v229, v45
	v_sub_f32_e32 v45, v56, v124
	v_add_f32_e32 v44, v225, v44
	v_exp_f32_e32 v230, v45
	v_sub_f32_e32 v45, v57, v124
	v_add_f32_e32 v44, v227, v44
	v_exp_f32_e32 v231, v45
	v_sub_f32_e32 v45, v58, v124
	v_add_f32_e32 v44, v228, v44
	v_exp_f32_e32 v232, v45
	v_sub_f32_e32 v45, v59, v124
	v_add_f32_e32 v44, v229, v44
	v_exp_f32_e32 v233, v45
	v_sub_f32_e32 v45, v60, v124
	v_add_f32_e32 v44, v230, v44
	v_exp_f32_e32 v217, v45
	v_sub_f32_e32 v45, v61, v124
	v_add_f32_e32 v44, v231, v44
	v_exp_f32_e32 v219, v45
	v_sub_f32_e32 v45, v62, v124
	v_add_f32_e32 v44, v232, v44
	v_exp_f32_e32 v220, v45
	v_sub_f32_e32 v45, v63, v124
	v_add_f32_e32 v44, v233, v44
	v_exp_f32_e32 v221, v45
	v_sub_f32_e32 v45, v64, v124
	v_add_f32_e32 v44, v217, v44
	v_exp_f32_e32 v222, v45
	v_sub_f32_e32 v45, v65, v124
	v_add_f32_e32 v44, v219, v44
	v_exp_f32_e32 v223, v45
	v_sub_f32_e32 v45, v66, v124
	v_add_f32_e32 v44, v220, v44
	v_exp_f32_e32 v224, v45
	v_sub_f32_e32 v45, v67, v124
	v_add_f32_e32 v44, v221, v44
	v_exp_f32_e32 v226, v45
	v_sub_f32_e32 v45, v68, v124
	v_add_f32_e32 v44, v222, v44
	v_exp_f32_e32 v125, v45
	v_sub_f32_e32 v45, v69, v124
	v_add_f32_e32 v44, v223, v44
	v_exp_f32_e32 v126, v45
	v_sub_f32_e32 v45, v70, v124
	v_add_f32_e32 v44, v224, v44
	v_exp_f32_e32 v127, v45
	v_sub_f32_e32 v45, v71, v124
	v_add_f32_e32 v44, v226, v44
	v_exp_f32_e32 v213, v45
	v_sub_f32_e32 v45, v72, v124
	v_add_f32_e32 v44, v125, v44
	v_exp_f32_e32 v214, v45
	v_sub_f32_e32 v45, v73, v124
	v_add_f32_e32 v44, v126, v44
	v_exp_f32_e32 v215, v45
	v_sub_f32_e32 v45, v74, v124
	v_add_f32_e32 v44, v127, v44
	v_exp_f32_e32 v216, v45
	v_sub_f32_e32 v45, v75, v124
	v_add_f32_e32 v44, v213, v44
	v_exp_f32_e32 v218, v45
	v_sub_f32_e32 v45, v76, v124
	v_add_f32_e32 v44, v214, v44
	v_exp_f32_e32 v69, v45
	v_sub_f32_e32 v45, v77, v124
	v_add_f32_e32 v44, v215, v44
	v_exp_f32_e32 v70, v45
	v_sub_f32_e32 v45, v78, v124
	v_add_f32_e32 v44, v216, v44
	v_exp_f32_e32 v71, v45
	v_sub_f32_e32 v45, v79, v124
	v_add_f32_e32 v44, v218, v44
	v_exp_f32_e32 v72, v45
	v_sub_f32_e32 v45, v80, v124
	v_add_f32_e32 v44, v69, v44
	v_exp_f32_e32 v73, v45
	v_sub_f32_e32 v45, v81, v124
	v_add_f32_e32 v44, v70, v44
	v_exp_f32_e32 v74, v45
	v_sub_f32_e32 v45, v82, v124
	v_add_f32_e32 v44, v71, v44
	v_exp_f32_e32 v75, v45
	v_sub_f32_e32 v45, v83, v124
	v_add_f32_e32 v44, v72, v44
	v_exp_f32_e32 v76, v45
	v_sub_f32_e32 v45, v84, v124
	v_add_f32_e32 v44, v73, v44
	v_exp_f32_e32 v61, v45
	v_sub_f32_e32 v45, v85, v124
	v_add_f32_e32 v44, v74, v44
	v_exp_f32_e32 v62, v45
	v_sub_f32_e32 v45, v86, v124
	v_add_f32_e32 v44, v75, v44
	v_exp_f32_e32 v63, v45
	v_sub_f32_e32 v45, v87, v124
	v_add_f32_e32 v44, v76, v44
	v_exp_f32_e32 v64, v45
	v_sub_f32_e32 v45, v88, v124
	v_add_f32_e32 v44, v61, v44
	v_exp_f32_e32 v65, v45
	v_sub_f32_e32 v45, v89, v124
	v_add_f32_e32 v44, v62, v44
	v_exp_f32_e32 v66, v45
	v_sub_f32_e32 v45, v90, v124
	v_add_f32_e32 v44, v63, v44
	v_exp_f32_e32 v67, v45
	v_sub_f32_e32 v45, v91, v124
	v_add_f32_e32 v44, v64, v44
	v_exp_f32_e32 v68, v45
	v_sub_f32_e32 v45, v92, v124
	v_add_f32_e32 v44, v65, v44
	v_exp_f32_e32 v52, v45
	v_sub_f32_e32 v45, v93, v124
	v_add_f32_e32 v44, v66, v44
	v_exp_f32_e32 v53, v45
	v_sub_f32_e32 v45, v94, v124
	v_add_f32_e32 v44, v67, v44
	v_exp_f32_e32 v54, v45
	v_sub_f32_e32 v45, v95, v124
	v_add_f32_e32 v44, v68, v44
	v_exp_f32_e32 v55, v45
	v_sub_f32_e32 v45, v96, v124
	v_add_f32_e32 v44, v52, v44
	v_exp_f32_e32 v56, v45
	v_sub_f32_e32 v45, v97, v124
	v_sub_f32_e32 v0, v0, v124
	v_add_f32_e32 v44, v53, v44
	v_exp_f32_e32 v57, v45
	v_sub_f32_e32 v45, v98, v124
	v_add_f32_e32 v44, v54, v44
	v_exp_f32_e32 v58, v45
	v_sub_f32_e32 v45, v99, v124
	v_exp_f32_e32 v0, v0
	v_add_f32_e32 v44, v55, v44
	v_exp_f32_e32 v59, v45
	ds_read_b64_tr_b16 v[84:85], v212 offset:2304
	ds_read_b64_tr_b16 v[82:83], v212
	ds_read_b64_tr_b16 v[86:87], v212 offset:32
	v_add_f32_e32 v44, v56, v44
	v_add_f32_e32 v44, v57, v44
	v_add_f32_e32 v44, v58, v44
	v_pk_mul_f32 v[30:31], v[30:31], v[0:1] op_sel_hi:[1,0]
	v_pk_mul_f32 v[28:29], v[28:29], v[0:1] op_sel_hi:[1,0]
	v_cvt_pk_bf16_f32 v78, v234, v235
	v_cvt_pk_bf16_f32 v79, v236, v238
	v_cvt_pk_bf16_f32 v80, v240, v241
	v_cvt_pk_bf16_f32 v81, v242, v243
	v_add_f32_e32 v45, v59, v44
	v_sub_f32_e32 v44, v100, v124
	s_waitcnt lgkmcnt(1)
	v_mfma_f32_16x16x32_bf16 v[28:31], v[82:85], v[78:81], v[28:31]
	ds_read_b64_tr_b16 v[88:89], v212 offset:2336
	ds_read_b64_tr_b16 v[82:83], v212 offset:64
	ds_read_b64_tr_b16 v[84:85], v212 offset:2368
	v_exp_f32_e32 v44, v44
	v_pk_mul_f32 v[38:39], v[38:39], v[0:1] op_sel_hi:[1,0]
	v_pk_mul_f32 v[36:37], v[36:37], v[0:1] op_sel_hi:[1,0]
	v_pk_mul_f32 v[34:35], v[34:35], v[0:1] op_sel_hi:[1,0]
	v_add_f32_e32 v46, v44, v45
	v_sub_f32_e32 v45, v101, v124
	s_waitcnt lgkmcnt(0)
; #define LAS __attribute__((address_space(3)))
; __device__ __forceinline__ s16x4 ds_tr(LAS unsigned char* a) { return __builtin_amdgcn_ds_read_tr16_b64_v4i16((LAS s16x4*)a); }
; __device__ __forceinline__ bf16x8 cat8(s16x4 lo, s16x4 hi) { return __builtin_shufflevector(lo, hi, 0, 1, 2, 3, 4, 5, 6, 7); }
; __device__ __forceinline__ f32x4 mfma16(bf16x8 a, bf16x8 b, f32x4 c) { return __builtin_amdgcn_mfma_f32_16x16x32_bf16(a, b, c, 0, 0, 0); }
; __device__ __forceinline__ bf16x8 pk8(f32x4 a, f32x4 b) { u32x4 w; w[0] = cvt_pk_bf16(a[0], a[1]); w[1] = cvt_pk_bf16(a[2], a[3]); w[2] = cvt_pk_bf16(b[0], b[1]); w[3] = cvt_pk_bf16(b[2], b[3]); return __builtin_bit_cast(bf16x8, w); }
; __device__ void ph_na2(const P& p, LAS unsigned char* lds) {
;     ...
;                 for (int kp = 0; kp < 8; ++kp) {
;                     const bf16x8 pf = pk8(sc[2 * kp], sc[2 * kp + 1]);
;                     LAS unsigned char* vb = hf ? (Vc + (32 * kp + 4 * g + qq) * VP + 8 * pp) : (Vl + ((((r0 + kp) % RING) * 64) + cstart + 4 * g + qq) * VP + 8 * pp);
; #pragma unroll
;                     for (int dt = 0; dt < 4; ++dt) { const s16x4 lo = ds_tr(vb + dt * 32), hi = ds_tr(vb + 16 * VP + dt * 32); o[dt] = mfma16(cat8(lo, hi), pf, o[dt]); }
;                     if (kp & 1) asm volatile("" ::: "memory");
;                 }
	v_mfma_f32_16x16x32_bf16 v[36:39], v[82:85], v[78:81], v[36:39]
	ds_read_b64_tr_b16 v[82:83], v212 offset:96
	ds_read_b64_tr_b16 v[84:85], v212 offset:2400
	v_exp_f32_e32 v45, v45
	v_pk_mul_f32 v[32:33], v[32:33], v[0:1] op_sel_hi:[1,0]
	v_pk_mul_f32 v[42:43], v[42:43], v[0:1] op_sel_hi:[1,0]
	v_pk_mul_f32 v[40:41], v[40:41], v[0:1] op_sel_hi:[1,0]
	v_add_f32_e32 v47, v45, v46
	v_sub_f32_e32 v46, v102, v124
	v_mfma_f32_16x16x32_bf16 v[32:35], v[86:89], v[78:81], v[32:35]
	v_exp_f32_e32 v46, v46
	v_cvt_pk_bf16_f32 v71, v71, v72
	v_cvt_pk_bf16_f32 v72, v73, v74
	s_waitcnt lgkmcnt(0)
	v_mfma_f32_16x16x32_bf16 v[40:43], v[82:85], v[78:81], v[40:43]
	ds_read_b64_tr_b16 v[84:85], v211 offset:2304
	ds_read_b64_tr_b16 v[82:83], v211
	ds_read_b64_tr_b16 v[86:87], v211 offset:32
	v_cvt_pk_bf16_f32 v78, v225, v227
	v_cvt_pk_bf16_f32 v79, v228, v229
	v_cvt_pk_bf16_f32 v80, v230, v231
	v_cvt_pk_bf16_f32 v81, v232, v233
	ds_read_b64_tr_b16 v[88:89], v211 offset:2336
	v_add_f32_e32 v48, v46, v47
	s_waitcnt lgkmcnt(2)
	v_mfma_f32_16x16x32_bf16 v[28:31], v[82:85], v[78:81], v[28:31]
	ds_read_b64_tr_b16 v[82:83], v211 offset:64
	ds_read_b64_tr_b16 v[84:85], v211 offset:2368
	v_sub_f32_e32 v47, v103, v124
	v_exp_f32_e32 v47, v47
	s_waitcnt lgkmcnt(0)
	v_mfma_f32_16x16x32_bf16 v[36:39], v[82:85], v[78:81], v[36:39]
	ds_read_b64_tr_b16 v[82:83], v211 offset:96
	ds_read_b64_tr_b16 v[84:85], v211 offset:2400
	v_add_f32_e32 v49, v47, v48
	v_sub_f32_e32 v48, v104, v124
	v_exp_f32_e32 v48, v48
	v_mfma_f32_16x16x32_bf16 v[32:35], v[86:89], v[78:81], v[32:35]
	v_cvt_pk_bf16_f32 v73, v75, v76
	v_add_f32_e32 v50, v48, v49
	v_sub_f32_e32 v49, v105, v124
	s_waitcnt lgkmcnt(0)
	v_mfma_f32_16x16x32_bf16 v[40:43], v[82:85], v[78:81], v[40:43]
	ds_read_b64_tr_b16 v[84:85], v210 offset:2304
	ds_read_b64_tr_b16 v[82:83], v210
	ds_read_b64_tr_b16 v[86:87], v210 offset:32
	v_exp_f32_e32 v49, v49
	v_cvt_pk_bf16_f32 v78, v217, v219
	v_cvt_pk_bf16_f32 v79, v220, v221
	v_cvt_pk_bf16_f32 v80, v222, v223
	v_cvt_pk_bf16_f32 v81, v224, v226
	ds_read_b64_tr_b16 v[88:89], v210 offset:2336
	v_add_f32_e32 v51, v49, v50
	s_waitcnt lgkmcnt(2)
	v_mfma_f32_16x16x32_bf16 v[28:31], v[82:85], v[78:81], v[28:31]
	ds_read_b64_tr_b16 v[82:83], v210 offset:64
	ds_read_b64_tr_b16 v[84:85], v210 offset:2368
	v_sub_f32_e32 v50, v106, v124
	v_exp_f32_e32 v50, v50
	s_waitcnt lgkmcnt(0)
	v_mfma_f32_16x16x32_bf16 v[36:39], v[82:85], v[78:81], v[36:39]
	ds_read_b64_tr_b16 v[82:83], v210 offset:96
	ds_read_b64_tr_b16 v[84:85], v210 offset:2400
	v_add_f32_e32 v60, v50, v51
	v_sub_f32_e32 v51, v107, v124
	v_exp_f32_e32 v51, v51
	v_mfma_f32_16x16x32_bf16 v[32:35], v[86:89], v[78:81], v[32:35]
	v_cvt_pk_bf16_f32 v70, v69, v70
	v_cvt_pk_bf16_f32 v63, v63, v64
	v_add_f32_e32 v60, v51, v60
	s_waitcnt lgkmcnt(0)
	v_mfma_f32_16x16x32_bf16 v[40:43], v[82:85], v[78:81], v[40:43]
	ds_read_b64_tr_b16 v[84:85], v209 offset:2304
	ds_read_b64_tr_b16 v[82:83], v209
	ds_read_b64_tr_b16 v[86:87], v209 offset:32
	ds_bpermute_b32 v77, v237, v60
	v_cvt_pk_bf16_f32 v78, v125, v126
	v_cvt_pk_bf16_f32 v79, v127, v213
	v_cvt_pk_bf16_f32 v80, v214, v215
	v_cvt_pk_bf16_f32 v81, v216, v218
	ds_read_b64_tr_b16 v[88:89], v209 offset:2336
	s_waitcnt lgkmcnt(1)
	v_add_f32_e32 v60, v60, v77
	v_mfma_f32_16x16x32_bf16 v[28:31], v[82:85], v[78:81], v[28:31]
	ds_read_b64_tr_b16 v[82:83], v209 offset:64
	ds_read_b64_tr_b16 v[84:85], v209 offset:2368
	ds_bpermute_b32 v77, v239, v60
	v_cvt_pk_bf16_f32 v64, v65, v66
	s_waitcnt lgkmcnt(1)
	v_mfma_f32_16x16x32_bf16 v[36:39], v[82:85], v[78:81], v[36:39]
	ds_read_b64_tr_b16 v[82:83], v209 offset:96
	ds_read_b64_tr_b16 v[84:85], v209 offset:2400
	s_waitcnt lgkmcnt(2)
	v_add_f32_e32 v60, v60, v77
	v_mfma_f32_16x16x32_bf16 v[32:35], v[86:89], v[78:81], v[32:35]
	v_cvt_pk_bf16_f32 v65, v67, v68
	v_cvt_pk_bf16_f32 v62, v61, v62
	v_cvt_pk_bf16_f32 v52, v52, v53
	s_waitcnt lgkmcnt(0)
	v_mfma_f32_16x16x32_bf16 v[40:43], v[82:85], v[78:81], v[40:43]
	ds_read_b64_tr_b16 v[76:77], v208 offset:2304
	ds_read_b64_tr_b16 v[74:75], v208
	ds_read_b64_tr_b16 v[78:79], v208 offset:32
	ds_read_b64_tr_b16 v[80:81], v208 offset:2336
	v_cvt_pk_bf16_f32 v53, v54, v55
	s_waitcnt lgkmcnt(2)
	v_mfma_f32_16x16x32_bf16 v[28:31], v[74:77], v[70:73], v[28:31]
	ds_read_b64_tr_b16 v[74:75], v208 offset:64
	ds_read_b64_tr_b16 v[76:77], v208 offset:2368
	v_cvt_pk_bf16_f32 v54, v56, v57
	v_cvt_pk_bf16_f32 v55, v58, v59
	s_waitcnt lgkmcnt(0)
	v_mfma_f32_16x16x32_bf16 v[36:39], v[74:77], v[70:73], v[36:39]
	ds_read_b64_tr_b16 v[74:75], v208 offset:96
	ds_read_b64_tr_b16 v[76:77], v208 offset:2400
	v_cvt_pk_bf16_f32 v44, v44, v45
	v_cvt_pk_bf16_f32 v45, v46, v47
	v_mfma_f32_16x16x32_bf16 v[32:35], v[78:81], v[70:73], v[32:35]
	v_cvt_pk_bf16_f32 v46, v48, v49
	v_cvt_pk_bf16_f32 v47, v50, v51
	v_fmac_f32_e32 v60, v189, v0
	s_waitcnt lgkmcnt(0)
	v_mfma_f32_16x16x32_bf16 v[40:43], v[74:77], v[70:73], v[40:43]
	ds_read_b64_tr_b16 v[68:69], v207 offset:2304
	ds_read_b64_tr_b16 v[66:67], v207
	ds_read_b64_tr_b16 v[70:71], v207 offset:32
	ds_read_b64_tr_b16 v[72:73], v207 offset:2336
	s_waitcnt lgkmcnt(2)
	v_mfma_f32_16x16x32_bf16 v[28:31], v[66:69], v[62:65], v[28:31]
	ds_read_b64_tr_b16 v[66:67], v207 offset:64
	ds_read_b64_tr_b16 v[68:69], v207 offset:2368
	s_waitcnt lgkmcnt(0)
	v_mfma_f32_16x16x32_bf16 v[36:39], v[66:69], v[62:65], v[36:39]
	ds_read_b64_tr_b16 v[66:67], v207 offset:96
	ds_read_b64_tr_b16 v[68:69], v207 offset:2400
	v_mfma_f32_16x16x32_bf16 v[32:35], v[70:73], v[62:65], v[32:35]
	s_waitcnt lgkmcnt(0)
	v_mfma_f32_16x16x32_bf16 v[40:43], v[66:69], v[62:65], v[40:43]
	ds_read_b64_tr_b16 v[58:59], v206 offset:2304
	ds_read_b64_tr_b16 v[56:57], v206
	ds_read_b64_tr_b16 v[62:63], v206 offset:32
	ds_read_b64_tr_b16 v[64:65], v206 offset:2336
	s_waitcnt lgkmcnt(2)
	v_mfma_f32_16x16x32_bf16 v[28:31], v[56:59], v[52:55], v[28:31]
	ds_read_b64_tr_b16 v[56:57], v206 offset:64
	ds_read_b64_tr_b16 v[58:59], v206 offset:2368
	s_waitcnt lgkmcnt(0)
	v_mfma_f32_16x16x32_bf16 v[36:39], v[56:59], v[52:55], v[36:39]
	ds_read_b64_tr_b16 v[56:57], v206 offset:96
	ds_read_b64_tr_b16 v[58:59], v206 offset:2400
	v_mfma_f32_16x16x32_bf16 v[32:35], v[62:65], v[52:55], v[32:35]
	s_waitcnt lgkmcnt(0)
	v_mfma_f32_16x16x32_bf16 v[40:43], v[56:59], v[52:55], v[40:43]
	ds_read_b64_tr_b16 v[50:51], v205 offset:2304
	ds_read_b64_tr_b16 v[48:49], v205
	ds_read_b64_tr_b16 v[52:53], v205 offset:32
	ds_read_b64_tr_b16 v[54:55], v205 offset:2336
	s_waitcnt lgkmcnt(2)
	v_mfma_f32_16x16x32_bf16 v[28:31], v[48:51], v[44:47], v[28:31]
	ds_read_b64_tr_b16 v[48:49], v205 offset:64
	ds_read_b64_tr_b16 v[50:51], v205 offset:2368
	s_waitcnt lgkmcnt(0)
	v_mfma_f32_16x16x32_bf16 v[36:39], v[48:51], v[44:47], v[36:39]
	ds_read_b64_tr_b16 v[48:49], v205 offset:96
	ds_read_b64_tr_b16 v[50:51], v205 offset:2400
	v_mfma_f32_16x16x32_bf16 v[32:35], v[52:55], v[44:47], v[32:35]
	s_waitcnt lgkmcnt(0)
	v_mfma_f32_16x16x32_bf16 v[40:43], v[48:51], v[44:47], v[40:43]
	s_cbranch_vccnz .LBB0_311
	v_mov_b32_e32 v189, v60
	v_mov_b32_e32 v0, v124
	s_branch .LBB0_345
